# adds: accumulators no longer zeroed with 128 v_mov per unit; peeled first K-loop iteration of all 4 GEMM loops uses srcC=0
# speedup vs baseline: 1.0254x; 1.0030x over previous
.LBB0_67:
	s_ashr_i32 s15, s14, 31
	s_lshl_b64 s[16:17], s[14:15], 19
	s_add_u32 s16, s30, s16
	s_addc_u32 s17, s31, s17
	s_and_b64 s[18:19], s[42:43], exec
	s_cselect_b32 s15, s17, s23
	s_cselect_b32 s21, s16, s22
	s_ashr_i32 s13, s12, 31
	s_lshl_b64 s[18:19], s[12:13], 19
	s_add_u32 s18, s34, s18
	s_addc_u32 s19, s35, s19
	s_and_b64 s[26:27], s[42:43], exec
	s_cselect_b32 s13, s19, s25
	s_cselect_b32 s33, s18, s24
	s_add_u32 s22, s22, 0x40080
	s_addc_u32 s23, s23, 0
	s_add_u32 s55, s24, 0x100
	s_addc_u32 s56, s25, 0
	s_mov_b32 s57, -2
	s_add_u32 s24, s22, 0xfffc0080
	s_addc_u32 s25, s23, -1
	s_add_i32 s60, 0, 0x10000
	s_cmp_eq_u32 s57, 12
	s_cselect_b32 s27, s15, s25
	s_cselect_b32 s26, s21, s24
	s_cselect_b32 s25, s13, s56
	s_cselect_b32 s24, s33, s55
	s_add_i32 s63, 0, 0x14000
	v_add_u32_e32 v154, s60, v172
	v_add_u32_e32 v176, s63, v172
	ds_read_b128 v[130:133], v154
	ds_read_b128 v[146:149], v154 offset:1024
	ds_read_b128 v[150:153], v154 offset:2048
	ds_read_b128 v[154:157], v154 offset:3072
	ds_read_b128 v[158:161], v176
	ds_read_b128 v[162:165], v176 offset:1024
	ds_read_b128 v[168:171], v176 offset:2048
	ds_read_b128 v[176:179], v176 offset:3072
	v_lshl_add_u64 v[208:209], s[22:23], 0, v[142:143]
	s_add_i32 m0, s37, 0xc000
	ds_read_b128 v[180:183], v175
	ds_read_b128 v[184:187], v175 offset:1024
	ds_read_b128 v[188:191], v175 offset:2048
	ds_read_b128 v[192:195], v175 offset:3072
	ds_read_b128 v[196:199], v175 offset:4096
	ds_read_b128 v[200:203], v175 offset:5120
	ds_read_b128 v[204:207], v175 offset:6144
	ds_read_b128 v[216:219], v175 offset:7168
	global_load_lds_dwordx4 v[208:209], off
	v_lshl_add_u64 v[208:209], s[22:23], 0, v[144:145]
	s_add_i32 m0, s37, 0xe000
	s_nop 0
	global_load_lds_dwordx4 v[208:209], off
	s_waitcnt vmcnt(8)
	s_waitcnt lgkmcnt(0)
	s_barrier
	s_setprio 1
	s_waitcnt lgkmcnt(0)
	v_mfma_f32_16x16x32_f16 v[126:129], v[130:133], v[180:183], 0
	v_mfma_f32_16x16x32_f16 v[118:121], v[150:153], v[180:183], 0
	v_mfma_f32_16x16x32_f16 v[110:113], v[130:133], v[188:191], 0
	v_mfma_f32_16x16x32_f16 v[102:105], v[150:153], v[188:191], 0
	v_mfma_f32_16x16x32_f16 v[92:95], v[130:133], v[196:199], 0
	v_mfma_f32_16x16x32_f16 v[84:87], v[150:153], v[196:199], 0
	v_mfma_f32_16x16x32_f16 v[76:79], v[130:133], v[204:207], 0
	v_mfma_f32_16x16x32_f16 v[68:71], v[150:153], v[204:207], 0
	v_mfma_f32_16x16x32_f16 v[126:129], v[146:149], v[184:187], v[126:129]
	v_mfma_f32_16x16x32_f16 v[118:121], v[154:157], v[184:187], v[118:121]
	v_mfma_f32_16x16x32_f16 v[110:113], v[146:149], v[192:195], v[110:113]
	v_mfma_f32_16x16x32_f16 v[102:105], v[154:157], v[192:195], v[102:105]
	v_mfma_f32_16x16x32_f16 v[92:95], v[146:149], v[200:203], v[92:95]
	v_mfma_f32_16x16x32_f16 v[84:87], v[154:157], v[200:203], v[84:87]
	v_mfma_f32_16x16x32_f16 v[76:79], v[146:149], v[216:219], v[76:79]
	v_mfma_f32_16x16x32_f16 v[68:71], v[154:157], v[216:219], v[68:71]
	v_mfma_f32_16x16x32_f16 v[122:125], v[158:161], v[180:183], 0
	v_mfma_f32_16x16x32_f16 v[114:117], v[168:171], v[180:183], 0
	v_mfma_f32_16x16x32_f16 v[106:109], v[158:161], v[188:191], 0
	v_mfma_f32_16x16x32_f16 v[98:101], v[168:171], v[188:191], 0
	v_mfma_f32_16x16x32_f16 v[88:91], v[158:161], v[196:199], 0
	v_mfma_f32_16x16x32_f16 v[80:83], v[168:171], v[196:199], 0
	v_mfma_f32_16x16x32_f16 v[72:75], v[158:161], v[204:207], 0
	v_mfma_f32_16x16x32_f16 v[64:67], v[168:171], v[204:207], 0
	v_mfma_f32_16x16x32_f16 v[122:125], v[162:165], v[184:187], v[122:125]
	v_mfma_f32_16x16x32_f16 v[114:117], v[176:179], v[184:187], v[114:117]
	v_mfma_f32_16x16x32_f16 v[106:109], v[162:165], v[192:195], v[106:109]
	v_mfma_f32_16x16x32_f16 v[98:101], v[176:179], v[192:195], v[98:101]
	v_mfma_f32_16x16x32_f16 v[88:91], v[162:165], v[200:203], v[88:91]
	v_mfma_f32_16x16x32_f16 v[80:83], v[176:179], v[200:203], v[80:83]
	v_mfma_f32_16x16x32_f16 v[72:75], v[162:165], v[216:219], v[72:75]
	v_mfma_f32_16x16x32_f16 v[64:67], v[176:179], v[216:219], v[64:67]
	s_setprio 0
	s_barrier
	s_add_i32 s60, s60, s29
	v_lshl_add_u64 v[208:209], s[24:25], 0, v[96:97]
	s_mov_b32 m0, s60
	ds_read_b128 v[180:183], v175 offset:16384
	ds_read_b128 v[184:187], v175 offset:17408
	ds_read_b128 v[188:191], v175 offset:18432
	ds_read_b128 v[192:195], v175 offset:19456
	ds_read_b128 v[196:199], v175 offset:20480
	ds_read_b128 v[200:203], v175 offset:21504
	ds_read_b128 v[204:207], v175 offset:22528
	ds_read_b128 v[216:219], v175 offset:23552
	global_load_lds_dwordx4 v[208:209], off
	s_add_i32 m0, s60, 0x2000
	s_add_u32 s60, s24, 0x40000
	v_lshl_add_u64 v[210:211], s[24:25], 0, v[134:135]
	s_addc_u32 s61, s25, 0
	s_add_i32 s63, s63, s29
	global_load_lds_dwordx4 v[210:211], off
	v_lshl_add_u64 v[212:213], s[60:61], 0, v[96:97]
	s_mov_b32 m0, s63
	v_lshl_add_u64 v[220:221], s[26:27], 0, v[136:137]
	global_load_lds_dwordx4 v[212:213], off
	v_lshl_add_u64 v[212:213], s[60:61], 0, v[134:135]
	s_add_i32 m0, s63, 0x2000
	s_nop 0
	global_load_lds_dwordx4 v[212:213], off
	v_lshl_add_u64 v[212:213], s[26:27], 0, v[138:139]
	s_mov_b32 m0, s37
	s_nop 0
	global_load_lds_dwordx4 v[212:213], off
	s_mov_b32 m0, s45
	s_nop 0
	global_load_lds_dwordx4 v[220:221], off
	s_waitcnt vmcnt(8)
	s_waitcnt lgkmcnt(0)
	s_barrier
	s_setprio 1
	s_waitcnt lgkmcnt(0)
	v_mfma_f32_16x16x32_f16 v[60:63], v[130:133], v[180:183], 0
	v_mfma_f32_16x16x32_f16 v[52:55], v[150:153], v[180:183], 0
	v_mfma_f32_16x16x32_f16 v[44:47], v[130:133], v[188:191], 0
	v_mfma_f32_16x16x32_f16 v[36:39], v[150:153], v[188:191], 0
	v_mfma_f32_16x16x32_f16 v[28:31], v[130:133], v[196:199], 0
	v_mfma_f32_16x16x32_f16 v[20:23], v[150:153], v[196:199], 0
	v_mfma_f32_16x16x32_f16 v[12:15], v[130:133], v[204:207], 0
	v_mfma_f32_16x16x32_f16 v[4:7], v[150:153], v[204:207], 0
	v_mfma_f32_16x16x32_f16 v[60:63], v[146:149], v[184:187], v[60:63]
	v_mfma_f32_16x16x32_f16 v[52:55], v[154:157], v[184:187], v[52:55]
	v_mfma_f32_16x16x32_f16 v[44:47], v[146:149], v[192:195], v[44:47]
	v_mfma_f32_16x16x32_f16 v[36:39], v[154:157], v[192:195], v[36:39]
	v_mfma_f32_16x16x32_f16 v[28:31], v[146:149], v[200:203], v[28:31]
	v_mfma_f32_16x16x32_f16 v[20:23], v[154:157], v[200:203], v[20:23]
	v_mfma_f32_16x16x32_f16 v[12:15], v[146:149], v[216:219], v[12:15]
	v_mfma_f32_16x16x32_f16 v[4:7], v[154:157], v[216:219], v[4:7]
	v_mfma_f32_16x16x32_f16 v[56:59], v[158:161], v[180:183], 0
	v_mfma_f32_16x16x32_f16 v[48:51], v[168:171], v[180:183], 0
	v_mfma_f32_16x16x32_f16 v[40:43], v[158:161], v[188:191], 0
	v_mfma_f32_16x16x32_f16 v[32:35], v[168:171], v[188:191], 0
	v_mfma_f32_16x16x32_f16 v[24:27], v[158:161], v[196:199], 0
	v_mfma_f32_16x16x32_f16 v[16:19], v[168:171], v[196:199], 0
	v_mfma_f32_16x16x32_f16 v[8:11], v[158:161], v[204:207], 0
	v_mfma_f32_16x16x32_f16 v[0:3], v[168:171], v[204:207], 0
	v_mfma_f32_16x16x32_f16 v[56:59], v[162:165], v[184:187], v[56:59]
	v_mfma_f32_16x16x32_f16 v[48:51], v[176:179], v[184:187], v[48:51]
	v_mfma_f32_16x16x32_f16 v[40:43], v[162:165], v[192:195], v[40:43]
	v_mfma_f32_16x16x32_f16 v[32:35], v[176:179], v[192:195], v[32:35]
	v_mfma_f32_16x16x32_f16 v[24:27], v[162:165], v[200:203], v[24:27]
	v_mfma_f32_16x16x32_f16 v[16:19], v[176:179], v[200:203], v[16:19]
	v_mfma_f32_16x16x32_f16 v[8:11], v[162:165], v[216:219], v[8:11]
	v_mfma_f32_16x16x32_f16 v[0:3], v[176:179], v[216:219], v[0:3]
	s_setprio 0
	s_barrier
	s_add_i32 s60, 0, 0x18000
	s_add_i32 s61, 0, 0x1c000
	v_add_u32_e32 v154, s60, v172
	v_add_u32_e32 v176, s61, v172
	ds_read_b128 v[130:133], v154
	ds_read_b128 v[146:149], v154 offset:1024
	ds_read_b128 v[150:153], v154 offset:2048
	ds_read_b128 v[154:157], v154 offset:3072
	ds_read_b128 v[158:161], v176
	ds_read_b128 v[162:165], v176 offset:1024
	ds_read_b128 v[168:171], v176 offset:2048
	ds_read_b128 v[176:179], v176 offset:3072
	s_add_u32 s26, s26, 0x40000
	s_addc_u32 s27, s27, 0
	s_mov_b32 m0, s46
	v_lshl_add_u64 v[222:223], s[26:27], 0, v[138:139]
	ds_read_b128 v[180:183], v175 offset:32768
	ds_read_b128 v[184:187], v175 offset:33792
	ds_read_b128 v[188:191], v175 offset:34816
	ds_read_b128 v[192:195], v175 offset:35840
	ds_read_b128 v[196:199], v175 offset:36864
	ds_read_b128 v[200:203], v175 offset:37888
	ds_read_b128 v[204:207], v175 offset:38912
	ds_read_b128 v[216:219], v175 offset:39936
	global_load_lds_dwordx4 v[222:223], off
	v_lshl_add_u64 v[222:223], s[26:27], 0, v[136:137]
	s_mov_b32 m0, s47
	s_nop 0
	global_load_lds_dwordx4 v[222:223], off
	s_waitcnt vmcnt(8)
	s_waitcnt lgkmcnt(0)
	s_barrier
	s_setprio 1
	s_waitcnt lgkmcnt(0)
	v_mfma_f32_16x16x32_f16 v[126:129], v[130:133], v[180:183], v[126:129]
	v_mfma_f32_16x16x32_f16 v[118:121], v[150:153], v[180:183], v[118:121]
	v_mfma_f32_16x16x32_f16 v[110:113], v[130:133], v[188:191], v[110:113]
	v_mfma_f32_16x16x32_f16 v[102:105], v[150:153], v[188:191], v[102:105]
	v_mfma_f32_16x16x32_f16 v[92:95], v[130:133], v[196:199], v[92:95]
	v_mfma_f32_16x16x32_f16 v[84:87], v[150:153], v[196:199], v[84:87]
	v_mfma_f32_16x16x32_f16 v[76:79], v[130:133], v[204:207], v[76:79]
	v_mfma_f32_16x16x32_f16 v[68:71], v[150:153], v[204:207], v[68:71]
	v_mfma_f32_16x16x32_f16 v[126:129], v[146:149], v[184:187], v[126:129]
	v_mfma_f32_16x16x32_f16 v[118:121], v[154:157], v[184:187], v[118:121]
	v_mfma_f32_16x16x32_f16 v[110:113], v[146:149], v[192:195], v[110:113]
	v_mfma_f32_16x16x32_f16 v[102:105], v[154:157], v[192:195], v[102:105]
	v_mfma_f32_16x16x32_f16 v[92:95], v[146:149], v[200:203], v[92:95]
	v_mfma_f32_16x16x32_f16 v[84:87], v[154:157], v[200:203], v[84:87]
	v_mfma_f32_16x16x32_f16 v[76:79], v[146:149], v[216:219], v[76:79]
	v_mfma_f32_16x16x32_f16 v[68:71], v[154:157], v[216:219], v[68:71]
	v_mfma_f32_16x16x32_f16 v[122:125], v[158:161], v[180:183], v[122:125]
	v_mfma_f32_16x16x32_f16 v[114:117], v[168:171], v[180:183], v[114:117]
	v_mfma_f32_16x16x32_f16 v[106:109], v[158:161], v[188:191], v[106:109]
	v_mfma_f32_16x16x32_f16 v[98:101], v[168:171], v[188:191], v[98:101]
	v_mfma_f32_16x16x32_f16 v[88:91], v[158:161], v[196:199], v[88:91]
	v_mfma_f32_16x16x32_f16 v[80:83], v[168:171], v[196:199], v[80:83]
	v_mfma_f32_16x16x32_f16 v[72:75], v[158:161], v[204:207], v[72:75]
	v_mfma_f32_16x16x32_f16 v[64:67], v[168:171], v[204:207], v[64:67]
	v_mfma_f32_16x16x32_f16 v[122:125], v[162:165], v[184:187], v[122:125]
	v_mfma_f32_16x16x32_f16 v[114:117], v[176:179], v[184:187], v[114:117]
	v_mfma_f32_16x16x32_f16 v[106:109], v[162:165], v[192:195], v[106:109]
	v_mfma_f32_16x16x32_f16 v[98:101], v[176:179], v[192:195], v[98:101]
	v_mfma_f32_16x16x32_f16 v[88:91], v[162:165], v[200:203], v[88:91]
	v_mfma_f32_16x16x32_f16 v[80:83], v[176:179], v[200:203], v[80:83]
	v_mfma_f32_16x16x32_f16 v[72:75], v[162:165], v[216:219], v[72:75]
	v_mfma_f32_16x16x32_f16 v[64:67], v[176:179], v[216:219], v[64:67]
	s_setprio 0
	s_barrier
	s_add_i32 s26, s60, s29
	v_lshl_add_u64 v[208:209], v[208:209], 0, s[94:95]
	s_mov_b32 m0, s26
	ds_read_b128 v[180:183], v175 offset:49152
	ds_read_b128 v[184:187], v175 offset:50176
	ds_read_b128 v[188:191], v175 offset:51200
	ds_read_b128 v[192:195], v175 offset:52224
	ds_read_b128 v[196:199], v175 offset:53248
	ds_read_b128 v[200:203], v175 offset:54272
	ds_read_b128 v[204:207], v175 offset:55296
	ds_read_b128 v[216:219], v175 offset:56320
	global_load_lds_dwordx4 v[208:209], off
	s_add_i32 m0, s26, 0x2000
	s_add_u32 s24, s24, 0x40080
	v_lshl_add_u64 v[208:209], v[210:211], 0, s[94:95]
	s_addc_u32 s25, s25, 0
	s_add_i32 s26, s61, s29
	global_load_lds_dwordx4 v[208:209], off
	v_lshl_add_u64 v[208:209], s[24:25], 0, v[96:97]
	s_mov_b32 m0, s26
	s_nop 0
	global_load_lds_dwordx4 v[208:209], off
	v_lshl_add_u64 v[208:209], s[24:25], 0, v[134:135]
	s_add_i32 m0, s26, 0x2000
	s_nop 0
	global_load_lds_dwordx4 v[208:209], off
	v_lshl_add_u64 v[208:209], v[212:213], 0, s[94:95]
	s_mov_b32 m0, s48
	s_nop 0
	global_load_lds_dwordx4 v[208:209], off
	v_lshl_add_u64 v[208:209], v[220:221], 0, s[94:95]
	s_mov_b32 m0, s49
	s_nop 0
	global_load_lds_dwordx4 v[208:209], off
	s_waitcnt vmcnt(8)
	s_waitcnt lgkmcnt(0)
	s_barrier
	s_setprio 1
	s_waitcnt lgkmcnt(0)
	v_mfma_f32_16x16x32_f16 v[60:63], v[130:133], v[180:183], v[60:63]
	v_mfma_f32_16x16x32_f16 v[52:55], v[150:153], v[180:183], v[52:55]
	v_mfma_f32_16x16x32_f16 v[44:47], v[130:133], v[188:191], v[44:47]
	v_mfma_f32_16x16x32_f16 v[36:39], v[150:153], v[188:191], v[36:39]
	v_mfma_f32_16x16x32_f16 v[28:31], v[130:133], v[196:199], v[28:31]
	v_mfma_f32_16x16x32_f16 v[20:23], v[150:153], v[196:199], v[20:23]
	v_mfma_f32_16x16x32_f16 v[12:15], v[130:133], v[204:207], v[12:15]
	v_mfma_f32_16x16x32_f16 v[4:7], v[150:153], v[204:207], v[4:7]
	v_mfma_f32_16x16x32_f16 v[60:63], v[146:149], v[184:187], v[60:63]
	v_mfma_f32_16x16x32_f16 v[52:55], v[154:157], v[184:187], v[52:55]
	v_mfma_f32_16x16x32_f16 v[44:47], v[146:149], v[192:195], v[44:47]
	v_mfma_f32_16x16x32_f16 v[36:39], v[154:157], v[192:195], v[36:39]
	v_mfma_f32_16x16x32_f16 v[28:31], v[146:149], v[200:203], v[28:31]
	v_mfma_f32_16x16x32_f16 v[20:23], v[154:157], v[200:203], v[20:23]
	v_mfma_f32_16x16x32_f16 v[12:15], v[146:149], v[216:219], v[12:15]
	v_mfma_f32_16x16x32_f16 v[4:7], v[154:157], v[216:219], v[4:7]
	v_mfma_f32_16x16x32_f16 v[56:59], v[158:161], v[180:183], v[56:59]
	v_mfma_f32_16x16x32_f16 v[48:51], v[168:171], v[180:183], v[48:51]
	v_mfma_f32_16x16x32_f16 v[40:43], v[158:161], v[188:191], v[40:43]
	v_mfma_f32_16x16x32_f16 v[32:35], v[168:171], v[188:191], v[32:35]
	v_mfma_f32_16x16x32_f16 v[24:27], v[158:161], v[196:199], v[24:27]
	v_mfma_f32_16x16x32_f16 v[16:19], v[168:171], v[196:199], v[16:19]
	v_mfma_f32_16x16x32_f16 v[8:11], v[158:161], v[204:207], v[8:11]
	v_mfma_f32_16x16x32_f16 v[0:3], v[168:171], v[204:207], v[0:3]
	v_mfma_f32_16x16x32_f16 v[56:59], v[162:165], v[184:187], v[56:59]
	v_mfma_f32_16x16x32_f16 v[48:51], v[176:179], v[184:187], v[48:51]
	v_mfma_f32_16x16x32_f16 v[40:43], v[162:165], v[192:195], v[40:43]
	v_mfma_f32_16x16x32_f16 v[32:35], v[176:179], v[192:195], v[32:35]
	v_mfma_f32_16x16x32_f16 v[24:27], v[162:165], v[200:203], v[24:27]
	v_mfma_f32_16x16x32_f16 v[16:19], v[176:179], v[200:203], v[16:19]
	v_mfma_f32_16x16x32_f16 v[8:11], v[162:165], v[216:219], v[8:11]
	v_mfma_f32_16x16x32_f16 v[0:3], v[176:179], v[216:219], v[0:3]
	s_setprio 0
	s_barrier
	s_add_i32 s57, s57, 2
	s_add_u32 s22, s22, 0x100
	s_addc_u32 s23, s23, 0
	s_add_u32 s55, s55, 0x100
	s_addc_u32 s56, s56, 0
	s_cmp_gt_u32 s57, 13
	s_cbranch_scc0 .LBB0_68
	s_branch .Lz68_exit

.Lz68_exit:
	s_and_b64 vcc, exec, s[10:11]
	s_cbranch_vccz .LBB0_71
	s_barrier

.LBB0_330:
	s_add_u32 s42, s56, 0x80
	s_addc_u32 s43, s57, 0
	s_add_u32 s56, s48, 0x100
	s_addc_u32 s57, s49, 0
	s_mov_b32 s48, 0
	s_add_i32 s80, s48, 2
	s_add_u32 s81, s42, 0x80
	s_addc_u32 s49, s43, 0
	s_add_i32 s84, 0, 0x10000
	s_cmp_eq_u32 s74, s48
	s_cselect_b32 s49, s35, s49
	s_cselect_b32 s48, s34, s81
	s_cselect_b32 s87, s37, s57
	s_cselect_b32 s86, s36, s56
	s_add_i32 s81, 0, 0x14000
	v_add_u32_e32 v142, s84, v186
	v_add_u32_e32 v170, s81, v186
	ds_read_b128 v[130:133], v142
	ds_read_b128 v[134:137], v142 offset:1024
	ds_read_b128 v[138:141], v142 offset:2048
	ds_read_b128 v[142:145], v142 offset:3072
	ds_read_b128 v[146:149], v170
	ds_read_b128 v[150:153], v170 offset:1024
	ds_read_b128 v[154:157], v170 offset:2048
	ds_read_b128 v[170:173], v170 offset:3072
	v_lshl_add_u64 v[210:211], s[42:43], 0, v[164:165]
	s_add_i32 m0, s45, 0xc000
	ds_read_b128 v[174:177], v188
	ds_read_b128 v[178:181], v188 offset:1024
	ds_read_b128 v[182:185], v188 offset:2048
	ds_read_b128 v[190:193], v188 offset:3072
	ds_read_b128 v[194:197], v188 offset:4096
	ds_read_b128 v[198:201], v188 offset:5120
	ds_read_b128 v[202:205], v188 offset:6144
	ds_read_b128 v[206:209], v188 offset:7168
	global_load_lds_dwordx4 v[210:211], off
	v_lshl_add_u64 v[210:211], s[42:43], 0, v[168:169]
	s_add_i32 m0, s45, 0xe000
	s_nop 0
	global_load_lds_dwordx4 v[210:211], off
	s_waitcnt vmcnt(8)
	s_waitcnt lgkmcnt(0)
	s_barrier
	s_setprio 1
	s_waitcnt lgkmcnt(0)
	v_mfma_f32_16x16x32_bf16 v[126:129], v[130:133], v[174:177], 0
	v_mfma_f32_16x16x32_bf16 v[122:125], v[138:141], v[174:177], 0
	v_mfma_f32_16x16x32_bf16 v[110:113], v[130:133], v[182:185], 0
	v_mfma_f32_16x16x32_bf16 v[106:109], v[138:141], v[182:185], 0
	v_mfma_f32_16x16x32_bf16 v[92:95], v[130:133], v[194:197], 0
	v_mfma_f32_16x16x32_bf16 v[88:91], v[138:141], v[194:197], 0
	v_mfma_f32_16x16x32_bf16 v[76:79], v[130:133], v[202:205], 0
	v_mfma_f32_16x16x32_bf16 v[72:75], v[138:141], v[202:205], 0
	v_mfma_f32_16x16x32_bf16 v[126:129], v[134:137], v[178:181], v[126:129]
	v_mfma_f32_16x16x32_bf16 v[122:125], v[142:145], v[178:181], v[122:125]
	v_mfma_f32_16x16x32_bf16 v[110:113], v[134:137], v[190:193], v[110:113]
	v_mfma_f32_16x16x32_bf16 v[106:109], v[142:145], v[190:193], v[106:109]
	v_mfma_f32_16x16x32_bf16 v[92:95], v[134:137], v[198:201], v[92:95]
	v_mfma_f32_16x16x32_bf16 v[88:91], v[142:145], v[198:201], v[88:91]
	v_mfma_f32_16x16x32_bf16 v[76:79], v[134:137], v[206:209], v[76:79]
	v_mfma_f32_16x16x32_bf16 v[72:75], v[142:145], v[206:209], v[72:75]
	v_mfma_f32_16x16x32_bf16 v[118:121], v[146:149], v[174:177], 0
	v_mfma_f32_16x16x32_bf16 v[114:117], v[154:157], v[174:177], 0
	v_mfma_f32_16x16x32_bf16 v[102:105], v[146:149], v[182:185], 0
	v_mfma_f32_16x16x32_bf16 v[98:101], v[154:157], v[182:185], 0
	v_mfma_f32_16x16x32_bf16 v[84:87], v[146:149], v[194:197], 0
	v_mfma_f32_16x16x32_bf16 v[80:83], v[154:157], v[194:197], 0
	v_mfma_f32_16x16x32_bf16 v[68:71], v[146:149], v[202:205], 0
	v_mfma_f32_16x16x32_bf16 v[64:67], v[154:157], v[202:205], 0
	v_mfma_f32_16x16x32_bf16 v[118:121], v[150:153], v[178:181], v[118:121]
	v_mfma_f32_16x16x32_bf16 v[114:117], v[170:173], v[178:181], v[114:117]
	v_mfma_f32_16x16x32_bf16 v[102:105], v[150:153], v[190:193], v[102:105]
	v_mfma_f32_16x16x32_bf16 v[98:101], v[170:173], v[190:193], v[98:101]
	v_mfma_f32_16x16x32_bf16 v[84:87], v[150:153], v[198:201], v[84:87]
	v_mfma_f32_16x16x32_bf16 v[80:83], v[170:173], v[198:201], v[80:83]
	v_mfma_f32_16x16x32_bf16 v[68:71], v[150:153], v[206:209], v[68:71]
	v_mfma_f32_16x16x32_bf16 v[64:67], v[170:173], v[206:209], v[64:67]
	s_setprio 0
	s_barrier
	s_add_i32 s84, s84, s8
	v_lshl_add_u64 v[210:211], s[86:87], 0, v[96:97]
	s_mov_b32 m0, s84
	ds_read_b128 v[174:177], v188 offset:16384
	ds_read_b128 v[178:181], v188 offset:17408
	ds_read_b128 v[182:185], v188 offset:18432
	ds_read_b128 v[190:193], v188 offset:19456
	ds_read_b128 v[194:197], v188 offset:20480
	ds_read_b128 v[198:201], v188 offset:21504
	ds_read_b128 v[202:205], v188 offset:22528
	ds_read_b128 v[206:209], v188 offset:23552
	global_load_lds_dwordx4 v[210:211], off
	s_add_i32 m0, s84, 0x2000
	v_lshl_add_u64 v[212:213], s[86:87], 0, v[162:163]
	s_add_u32 s86, s86, s16
	s_addc_u32 s87, s87, 0
	s_add_i32 s81, s81, s8
	global_load_lds_dwordx4 v[212:213], off
	v_lshl_add_u64 v[216:217], s[86:87], 0, v[96:97]
	s_mov_b32 m0, s81
	v_lshl_add_u64 v[218:219], s[86:87], 0, v[162:163]
	global_load_lds_dwordx4 v[216:217], off
	s_add_i32 m0, s81, 0x2000
	v_lshl_add_u64 v[220:221], s[48:49], 0, v[158:159]
	global_load_lds_dwordx4 v[218:219], off
	s_mov_b32 m0, s45
	v_lshl_add_u64 v[222:223], s[48:49], 0, v[160:161]
	global_load_lds_dwordx4 v[220:221], off
	s_mov_b32 m0, s55
	s_nop 0
	global_load_lds_dwordx4 v[222:223], off
	s_waitcnt vmcnt(8)
	s_waitcnt lgkmcnt(0)
	s_barrier
	s_setprio 1
	s_waitcnt lgkmcnt(0)
	v_mfma_f32_16x16x32_bf16 v[60:63], v[130:133], v[174:177], 0
	v_mfma_f32_16x16x32_bf16 v[56:59], v[138:141], v[174:177], 0
	v_mfma_f32_16x16x32_bf16 v[44:47], v[130:133], v[182:185], 0
	v_mfma_f32_16x16x32_bf16 v[40:43], v[138:141], v[182:185], 0
	v_mfma_f32_16x16x32_bf16 v[28:31], v[130:133], v[194:197], 0
	v_mfma_f32_16x16x32_bf16 v[24:27], v[138:141], v[194:197], 0
	v_mfma_f32_16x16x32_bf16 v[12:15], v[130:133], v[202:205], 0
	v_mfma_f32_16x16x32_bf16 v[8:11], v[138:141], v[202:205], 0
	v_mfma_f32_16x16x32_bf16 v[60:63], v[134:137], v[178:181], v[60:63]
	v_mfma_f32_16x16x32_bf16 v[56:59], v[142:145], v[178:181], v[56:59]
	v_mfma_f32_16x16x32_bf16 v[44:47], v[134:137], v[190:193], v[44:47]
	v_mfma_f32_16x16x32_bf16 v[40:43], v[142:145], v[190:193], v[40:43]
	v_mfma_f32_16x16x32_bf16 v[28:31], v[134:137], v[198:201], v[28:31]
	v_mfma_f32_16x16x32_bf16 v[24:27], v[142:145], v[198:201], v[24:27]
	v_mfma_f32_16x16x32_bf16 v[12:15], v[134:137], v[206:209], v[12:15]
	v_mfma_f32_16x16x32_bf16 v[8:11], v[142:145], v[206:209], v[8:11]
	v_mfma_f32_16x16x32_bf16 v[52:55], v[146:149], v[174:177], 0
	v_mfma_f32_16x16x32_bf16 v[48:51], v[154:157], v[174:177], 0
	v_mfma_f32_16x16x32_bf16 v[36:39], v[146:149], v[182:185], 0
	v_mfma_f32_16x16x32_bf16 v[32:35], v[154:157], v[182:185], 0
	v_mfma_f32_16x16x32_bf16 v[20:23], v[146:149], v[194:197], 0
	v_mfma_f32_16x16x32_bf16 v[16:19], v[154:157], v[194:197], 0
	v_mfma_f32_16x16x32_bf16 v[4:7], v[146:149], v[202:205], 0
	v_mfma_f32_16x16x32_bf16 v[0:3], v[154:157], v[202:205], 0
	v_mfma_f32_16x16x32_bf16 v[52:55], v[150:153], v[178:181], v[52:55]
	v_mfma_f32_16x16x32_bf16 v[48:51], v[170:173], v[178:181], v[48:51]
	v_mfma_f32_16x16x32_bf16 v[36:39], v[150:153], v[190:193], v[36:39]
	v_mfma_f32_16x16x32_bf16 v[32:35], v[170:173], v[190:193], v[32:35]
	v_mfma_f32_16x16x32_bf16 v[20:23], v[150:153], v[198:201], v[20:23]
	v_mfma_f32_16x16x32_bf16 v[16:19], v[170:173], v[198:201], v[16:19]
	v_mfma_f32_16x16x32_bf16 v[4:7], v[150:153], v[206:209], v[4:7]
	v_mfma_f32_16x16x32_bf16 v[0:3], v[170:173], v[206:209], v[0:3]
	s_setprio 0
	s_barrier
	s_add_i32 s81, 0, 0x18000
	s_add_i32 s84, 0, 0x1c000
	v_add_u32_e32 v142, s81, v186
	v_add_u32_e32 v170, s84, v186
	ds_read_b128 v[130:133], v142
	ds_read_b128 v[134:137], v142 offset:1024
	ds_read_b128 v[138:141], v142 offset:2048
	ds_read_b128 v[142:145], v142 offset:3072
	ds_read_b128 v[146:149], v170
	ds_read_b128 v[150:153], v170 offset:1024
	ds_read_b128 v[154:157], v170 offset:2048
	ds_read_b128 v[170:173], v170 offset:3072
	s_add_u32 s48, s48, s16
	s_addc_u32 s49, s49, 0
	s_mov_b32 m0, s60
	v_lshl_add_u64 v[224:225], s[48:49], 0, v[158:159]
	ds_read_b128 v[174:177], v188 offset:32768
	ds_read_b128 v[178:181], v188 offset:33792
	ds_read_b128 v[182:185], v188 offset:34816
	ds_read_b128 v[190:193], v188 offset:35840
	ds_read_b128 v[194:197], v188 offset:36864
	ds_read_b128 v[198:201], v188 offset:37888
	ds_read_b128 v[202:205], v188 offset:38912
	ds_read_b128 v[206:209], v188 offset:39936
	global_load_lds_dwordx4 v[224:225], off
	v_lshl_add_u64 v[224:225], s[48:49], 0, v[160:161]
	s_mov_b32 m0, s61
	s_nop 0
	global_load_lds_dwordx4 v[224:225], off
	s_waitcnt vmcnt(8)
	s_waitcnt lgkmcnt(0)
	s_barrier
	s_setprio 1
	s_waitcnt lgkmcnt(0)
	v_mfma_f32_16x16x32_bf16 v[126:129], v[130:133], v[174:177], v[126:129]
	v_mfma_f32_16x16x32_bf16 v[122:125], v[138:141], v[174:177], v[122:125]
	v_mfma_f32_16x16x32_bf16 v[110:113], v[130:133], v[182:185], v[110:113]
	v_mfma_f32_16x16x32_bf16 v[106:109], v[138:141], v[182:185], v[106:109]
	v_mfma_f32_16x16x32_bf16 v[92:95], v[130:133], v[194:197], v[92:95]
	v_mfma_f32_16x16x32_bf16 v[88:91], v[138:141], v[194:197], v[88:91]
	v_mfma_f32_16x16x32_bf16 v[76:79], v[130:133], v[202:205], v[76:79]
	v_mfma_f32_16x16x32_bf16 v[72:75], v[138:141], v[202:205], v[72:75]
	v_mfma_f32_16x16x32_bf16 v[126:129], v[134:137], v[178:181], v[126:129]
	v_mfma_f32_16x16x32_bf16 v[122:125], v[142:145], v[178:181], v[122:125]
	v_mfma_f32_16x16x32_bf16 v[110:113], v[134:137], v[190:193], v[110:113]
	v_mfma_f32_16x16x32_bf16 v[106:109], v[142:145], v[190:193], v[106:109]
	v_mfma_f32_16x16x32_bf16 v[92:95], v[134:137], v[198:201], v[92:95]
	v_mfma_f32_16x16x32_bf16 v[88:91], v[142:145], v[198:201], v[88:91]
	v_mfma_f32_16x16x32_bf16 v[76:79], v[134:137], v[206:209], v[76:79]
	v_mfma_f32_16x16x32_bf16 v[72:75], v[142:145], v[206:209], v[72:75]
	v_mfma_f32_16x16x32_bf16 v[118:121], v[146:149], v[174:177], v[118:121]
	v_mfma_f32_16x16x32_bf16 v[114:117], v[154:157], v[174:177], v[114:117]
	v_mfma_f32_16x16x32_bf16 v[102:105], v[146:149], v[182:185], v[102:105]
	v_mfma_f32_16x16x32_bf16 v[98:101], v[154:157], v[182:185], v[98:101]
	v_mfma_f32_16x16x32_bf16 v[84:87], v[146:149], v[194:197], v[84:87]
	v_mfma_f32_16x16x32_bf16 v[80:83], v[154:157], v[194:197], v[80:83]
	v_mfma_f32_16x16x32_bf16 v[68:71], v[146:149], v[202:205], v[68:71]
	v_mfma_f32_16x16x32_bf16 v[64:67], v[154:157], v[202:205], v[64:67]
	v_mfma_f32_16x16x32_bf16 v[118:121], v[150:153], v[178:181], v[118:121]
	v_mfma_f32_16x16x32_bf16 v[114:117], v[170:173], v[178:181], v[114:117]
	v_mfma_f32_16x16x32_bf16 v[102:105], v[150:153], v[190:193], v[102:105]
	v_mfma_f32_16x16x32_bf16 v[98:101], v[170:173], v[190:193], v[98:101]
	v_mfma_f32_16x16x32_bf16 v[84:87], v[150:153], v[198:201], v[84:87]
	v_mfma_f32_16x16x32_bf16 v[80:83], v[170:173], v[198:201], v[80:83]
	v_mfma_f32_16x16x32_bf16 v[68:71], v[150:153], v[206:209], v[68:71]
	v_mfma_f32_16x16x32_bf16 v[64:67], v[170:173], v[206:209], v[64:67]
	s_setprio 0
	s_barrier
	s_add_i32 s48, s81, s8
	v_lshl_add_u64 v[210:211], v[210:211], 0, s[94:95]
	s_mov_b32 m0, s48
	ds_read_b128 v[174:177], v188 offset:49152
	ds_read_b128 v[178:181], v188 offset:50176
	ds_read_b128 v[182:185], v188 offset:51200
	ds_read_b128 v[190:193], v188 offset:52224
	ds_read_b128 v[194:197], v188 offset:53248
	ds_read_b128 v[198:201], v188 offset:54272
	ds_read_b128 v[202:205], v188 offset:55296
	ds_read_b128 v[206:209], v188 offset:56320
	global_load_lds_dwordx4 v[210:211], off
	v_lshl_add_u64 v[210:211], v[212:213], 0, s[94:95]
	s_add_i32 m0, s48, 0x2000
	s_add_i32 s48, s84, s8
	global_load_lds_dwordx4 v[210:211], off
	v_lshl_add_u64 v[210:211], v[216:217], 0, s[94:95]
	s_mov_b32 m0, s48
	s_nop 0
	global_load_lds_dwordx4 v[210:211], off
	v_lshl_add_u64 v[210:211], v[218:219], 0, s[94:95]
	s_add_i32 m0, s48, 0x2000
	s_nop 0
	global_load_lds_dwordx4 v[210:211], off
	v_lshl_add_u64 v[210:211], v[220:221], 0, s[94:95]
	s_mov_b32 m0, s70
	s_nop 0
	global_load_lds_dwordx4 v[210:211], off
	v_lshl_add_u64 v[210:211], v[222:223], 0, s[94:95]
	s_mov_b32 m0, s73
	s_nop 0
	global_load_lds_dwordx4 v[210:211], off
	s_waitcnt vmcnt(8)
	s_waitcnt lgkmcnt(0)
	s_barrier
	s_setprio 1
	s_waitcnt lgkmcnt(0)
	v_mfma_f32_16x16x32_bf16 v[60:63], v[130:133], v[174:177], v[60:63]
	v_mfma_f32_16x16x32_bf16 v[56:59], v[138:141], v[174:177], v[56:59]
	v_mfma_f32_16x16x32_bf16 v[44:47], v[130:133], v[182:185], v[44:47]
	v_mfma_f32_16x16x32_bf16 v[40:43], v[138:141], v[182:185], v[40:43]
	v_mfma_f32_16x16x32_bf16 v[28:31], v[130:133], v[194:197], v[28:31]
	v_mfma_f32_16x16x32_bf16 v[24:27], v[138:141], v[194:197], v[24:27]
	v_mfma_f32_16x16x32_bf16 v[12:15], v[130:133], v[202:205], v[12:15]
	v_mfma_f32_16x16x32_bf16 v[8:11], v[138:141], v[202:205], v[8:11]
	v_mfma_f32_16x16x32_bf16 v[60:63], v[134:137], v[178:181], v[60:63]
	v_mfma_f32_16x16x32_bf16 v[56:59], v[142:145], v[178:181], v[56:59]
	v_mfma_f32_16x16x32_bf16 v[44:47], v[134:137], v[190:193], v[44:47]
	v_mfma_f32_16x16x32_bf16 v[40:43], v[142:145], v[190:193], v[40:43]
	v_mfma_f32_16x16x32_bf16 v[28:31], v[134:137], v[198:201], v[28:31]
	v_mfma_f32_16x16x32_bf16 v[24:27], v[142:145], v[198:201], v[24:27]
	v_mfma_f32_16x16x32_bf16 v[12:15], v[134:137], v[206:209], v[12:15]
	v_mfma_f32_16x16x32_bf16 v[8:11], v[142:145], v[206:209], v[8:11]
	v_mfma_f32_16x16x32_bf16 v[52:55], v[146:149], v[174:177], v[52:55]
	v_mfma_f32_16x16x32_bf16 v[48:51], v[154:157], v[174:177], v[48:51]
	v_mfma_f32_16x16x32_bf16 v[36:39], v[146:149], v[182:185], v[36:39]
	v_mfma_f32_16x16x32_bf16 v[32:35], v[154:157], v[182:185], v[32:35]
	v_mfma_f32_16x16x32_bf16 v[20:23], v[146:149], v[194:197], v[20:23]
	v_mfma_f32_16x16x32_bf16 v[16:19], v[154:157], v[194:197], v[16:19]
	v_mfma_f32_16x16x32_bf16 v[4:7], v[146:149], v[202:205], v[4:7]
	v_mfma_f32_16x16x32_bf16 v[0:3], v[154:157], v[202:205], v[0:3]
	v_mfma_f32_16x16x32_bf16 v[52:55], v[150:153], v[178:181], v[52:55]
	v_mfma_f32_16x16x32_bf16 v[48:51], v[170:173], v[178:181], v[48:51]
	v_mfma_f32_16x16x32_bf16 v[36:39], v[150:153], v[190:193], v[36:39]
	v_mfma_f32_16x16x32_bf16 v[32:35], v[170:173], v[190:193], v[32:35]
	v_mfma_f32_16x16x32_bf16 v[20:23], v[150:153], v[198:201], v[20:23]
	v_mfma_f32_16x16x32_bf16 v[16:19], v[170:173], v[198:201], v[16:19]
	v_mfma_f32_16x16x32_bf16 v[4:7], v[150:153], v[206:209], v[4:7]
	v_mfma_f32_16x16x32_bf16 v[0:3], v[170:173], v[206:209], v[0:3]
	s_setprio 0
	s_barrier
	s_add_u32 s42, s42, 0x100
	s_addc_u32 s43, s43, 0
	s_add_u32 s56, s56, 0x100
	s_addc_u32 s57, s57, 0
	s_cmp_ge_u32 s80, s69
	s_mov_b32 s48, s80
	s_cbranch_scc0 .LBB0_331
	s_branch .Lz331_exit

.Lz331_exit:
	s_and_b64 vcc, exec, s[28:29]
	s_cbranch_vccz .LBB0_334
	s_barrier

.LBB0_510:
	s_add_u32 s36, s36, 0x80
	s_addc_u32 s37, s37, 0
	s_add_u32 s48, s48, 0x100
	s_addc_u32 s49, s49, 0
	s_mov_b32 s46, 0
	s_add_i32 s84, s46, 2
	s_add_u32 s86, s36, 0x80
	s_addc_u32 s47, s37, 0
	s_add_i32 vcc_lo, 0, 0x10000
	s_cmp_eq_u32 s33, s46
	s_cselect_b32 s47, s31, s47
	s_cselect_b32 s46, s30, s86
	s_cselect_b32 s87, s35, s49
	s_cselect_b32 s86, s34, s48
	s_add_i32 vcc_hi, 0, 0x14000
	v_add_u32_e32 v154, vcc_lo, v174
	v_add_u32_e32 v172, vcc_hi, v174
	ds_read_b128 v[142:145], v154
	ds_read_b128 v[146:149], v154 offset:1024
	ds_read_b128 v[150:153], v154 offset:2048
	ds_read_b128 v[154:157], v154 offset:3072
	ds_read_b128 v[158:161], v172
	ds_read_b128 v[162:165], v172 offset:1024
	ds_read_b128 v[168:171], v172 offset:2048
	ds_read_b128 v[178:181], v172 offset:3072
	v_lshl_add_u64 v[172:173], s[36:37], 0, v[138:139]
	s_add_i32 m0, s75, 0xc000
	ds_read_b128 v[182:185], v177
	ds_read_b128 v[186:189], v177 offset:1024
	ds_read_b128 v[190:193], v177 offset:2048
	ds_read_b128 v[194:197], v177 offset:3072
	ds_read_b128 v[198:201], v177 offset:4096
	ds_read_b128 v[202:205], v177 offset:5120
	ds_read_b128 v[206:209], v177 offset:6144
	ds_read_b128 v[216:219], v177 offset:7168
	global_load_lds_dwordx4 v[172:173], off
	v_lshl_add_u64 v[172:173], s[36:37], 0, v[140:141]
	s_add_i32 m0, s75, 0xe000
	s_nop 0
	global_load_lds_dwordx4 v[172:173], off
	s_waitcnt vmcnt(8)
	s_waitcnt lgkmcnt(0)
	s_barrier
	s_setprio 1
	s_waitcnt lgkmcnt(0)
	v_mfma_f32_16x16x32_bf16 v[126:129], v[142:145], v[182:185], 0
	v_mfma_f32_16x16x32_bf16 v[122:125], v[150:153], v[182:185], 0
	v_mfma_f32_16x16x32_bf16 v[110:113], v[142:145], v[190:193], 0
	v_mfma_f32_16x16x32_bf16 v[106:109], v[150:153], v[190:193], 0
	v_mfma_f32_16x16x32_bf16 v[92:95], v[142:145], v[198:201], 0
	v_mfma_f32_16x16x32_bf16 v[88:91], v[150:153], v[198:201], 0
	v_mfma_f32_16x16x32_bf16 v[76:79], v[142:145], v[206:209], 0
	v_mfma_f32_16x16x32_bf16 v[72:75], v[150:153], v[206:209], 0
	v_mfma_f32_16x16x32_bf16 v[126:129], v[146:149], v[186:189], v[126:129]
	v_mfma_f32_16x16x32_bf16 v[122:125], v[154:157], v[186:189], v[122:125]
	v_mfma_f32_16x16x32_bf16 v[110:113], v[146:149], v[194:197], v[110:113]
	v_mfma_f32_16x16x32_bf16 v[106:109], v[154:157], v[194:197], v[106:109]
	v_mfma_f32_16x16x32_bf16 v[92:95], v[146:149], v[202:205], v[92:95]
	v_mfma_f32_16x16x32_bf16 v[88:91], v[154:157], v[202:205], v[88:91]
	v_mfma_f32_16x16x32_bf16 v[76:79], v[146:149], v[216:219], v[76:79]
	v_mfma_f32_16x16x32_bf16 v[72:75], v[154:157], v[216:219], v[72:75]
	v_mfma_f32_16x16x32_bf16 v[118:121], v[158:161], v[182:185], 0
	v_mfma_f32_16x16x32_bf16 v[114:117], v[168:171], v[182:185], 0
	v_mfma_f32_16x16x32_bf16 v[102:105], v[158:161], v[190:193], 0
	v_mfma_f32_16x16x32_bf16 v[98:101], v[168:171], v[190:193], 0
	v_mfma_f32_16x16x32_bf16 v[84:87], v[158:161], v[198:201], 0
	v_mfma_f32_16x16x32_bf16 v[80:83], v[168:171], v[198:201], 0
	v_mfma_f32_16x16x32_bf16 v[68:71], v[158:161], v[206:209], 0
	v_mfma_f32_16x16x32_bf16 v[64:67], v[168:171], v[206:209], 0
	v_mfma_f32_16x16x32_bf16 v[118:121], v[162:165], v[186:189], v[118:121]
	v_mfma_f32_16x16x32_bf16 v[114:117], v[178:181], v[186:189], v[114:117]
	v_mfma_f32_16x16x32_bf16 v[102:105], v[162:165], v[194:197], v[102:105]
	v_mfma_f32_16x16x32_bf16 v[98:101], v[178:181], v[194:197], v[98:101]
	v_mfma_f32_16x16x32_bf16 v[84:87], v[162:165], v[202:205], v[84:87]
	v_mfma_f32_16x16x32_bf16 v[80:83], v[178:181], v[202:205], v[80:83]
	v_mfma_f32_16x16x32_bf16 v[68:71], v[162:165], v[216:219], v[68:71]
	v_mfma_f32_16x16x32_bf16 v[64:67], v[178:181], v[216:219], v[64:67]
	s_setprio 0
	s_barrier
	s_add_i32 vcc_lo, vcc_lo, s71
	v_lshl_add_u64 v[172:173], s[86:87], 0, v[96:97]
	s_mov_b32 m0, vcc_lo
	ds_read_b128 v[182:185], v177 offset:16384
	ds_read_b128 v[186:189], v177 offset:17408
	ds_read_b128 v[190:193], v177 offset:18432
	ds_read_b128 v[194:197], v177 offset:19456
	ds_read_b128 v[198:201], v177 offset:20480
	ds_read_b128 v[202:205], v177 offset:21504
	ds_read_b128 v[206:209], v177 offset:22528
	ds_read_b128 v[216:219], v177 offset:23552
	global_load_lds_dwordx4 v[172:173], off
	s_add_i32 m0, vcc_lo, 0x2000
	v_lshl_add_u64 v[210:211], s[86:87], 0, v[134:135]
	s_add_u32 s86, s86, s8
	s_addc_u32 s87, s87, 0
	s_add_i32 vcc_lo, vcc_hi, s71
	global_load_lds_dwordx4 v[210:211], off
	v_lshl_add_u64 v[212:213], s[86:87], 0, v[96:97]
	s_mov_b32 m0, vcc_lo
	v_lshl_add_u64 v[220:221], s[86:87], 0, v[134:135]
	global_load_lds_dwordx4 v[212:213], off
	s_add_i32 m0, vcc_lo, 0x2000
	v_lshl_add_u64 v[222:223], s[46:47], 0, v[130:131]
	global_load_lds_dwordx4 v[220:221], off
	s_mov_b32 m0, s75
	v_lshl_add_u64 v[224:225], s[46:47], 0, v[132:133]
	global_load_lds_dwordx4 v[222:223], off
	s_mov_b32 m0, s76
	s_nop 0
	global_load_lds_dwordx4 v[224:225], off
	s_waitcnt vmcnt(8)
	s_waitcnt lgkmcnt(0)
	s_barrier
	s_setprio 1
	s_waitcnt lgkmcnt(0)
	v_mfma_f32_16x16x32_bf16 v[60:63], v[142:145], v[182:185], 0
	v_mfma_f32_16x16x32_bf16 v[56:59], v[150:153], v[182:185], 0
	v_mfma_f32_16x16x32_bf16 v[44:47], v[142:145], v[190:193], 0
	v_mfma_f32_16x16x32_bf16 v[40:43], v[150:153], v[190:193], 0
	v_mfma_f32_16x16x32_bf16 v[28:31], v[142:145], v[198:201], 0
	v_mfma_f32_16x16x32_bf16 v[24:27], v[150:153], v[198:201], 0
	v_mfma_f32_16x16x32_bf16 v[12:15], v[142:145], v[206:209], 0
	v_mfma_f32_16x16x32_bf16 v[8:11], v[150:153], v[206:209], 0
	v_mfma_f32_16x16x32_bf16 v[60:63], v[146:149], v[186:189], v[60:63]
	v_mfma_f32_16x16x32_bf16 v[56:59], v[154:157], v[186:189], v[56:59]
	v_mfma_f32_16x16x32_bf16 v[44:47], v[146:149], v[194:197], v[44:47]
	v_mfma_f32_16x16x32_bf16 v[40:43], v[154:157], v[194:197], v[40:43]
	v_mfma_f32_16x16x32_bf16 v[28:31], v[146:149], v[202:205], v[28:31]
	v_mfma_f32_16x16x32_bf16 v[24:27], v[154:157], v[202:205], v[24:27]
	v_mfma_f32_16x16x32_bf16 v[12:15], v[146:149], v[216:219], v[12:15]
	v_mfma_f32_16x16x32_bf16 v[8:11], v[154:157], v[216:219], v[8:11]
	v_mfma_f32_16x16x32_bf16 v[52:55], v[158:161], v[182:185], 0
	v_mfma_f32_16x16x32_bf16 v[48:51], v[168:171], v[182:185], 0
	v_mfma_f32_16x16x32_bf16 v[36:39], v[158:161], v[190:193], 0
	v_mfma_f32_16x16x32_bf16 v[32:35], v[168:171], v[190:193], 0
	v_mfma_f32_16x16x32_bf16 v[20:23], v[158:161], v[198:201], 0
	v_mfma_f32_16x16x32_bf16 v[16:19], v[168:171], v[198:201], 0
	v_mfma_f32_16x16x32_bf16 v[4:7], v[158:161], v[206:209], 0
	v_mfma_f32_16x16x32_bf16 v[0:3], v[168:171], v[206:209], 0
	v_mfma_f32_16x16x32_bf16 v[52:55], v[162:165], v[186:189], v[52:55]
	v_mfma_f32_16x16x32_bf16 v[48:51], v[178:181], v[186:189], v[48:51]
	v_mfma_f32_16x16x32_bf16 v[36:39], v[162:165], v[194:197], v[36:39]
	v_mfma_f32_16x16x32_bf16 v[32:35], v[178:181], v[194:197], v[32:35]
	v_mfma_f32_16x16x32_bf16 v[20:23], v[162:165], v[202:205], v[20:23]
	v_mfma_f32_16x16x32_bf16 v[16:19], v[178:181], v[202:205], v[16:19]
	v_mfma_f32_16x16x32_bf16 v[4:7], v[162:165], v[216:219], v[4:7]
	v_mfma_f32_16x16x32_bf16 v[0:3], v[178:181], v[216:219], v[0:3]
	s_setprio 0
	s_barrier
	s_add_i32 s86, 0, 0x18000
	s_add_i32 s87, 0, 0x1c000
	v_add_u32_e32 v154, s86, v174
	v_add_u32_e32 v178, s87, v174
	ds_read_b128 v[142:145], v154
	ds_read_b128 v[146:149], v154 offset:1024
	ds_read_b128 v[150:153], v154 offset:2048
	ds_read_b128 v[154:157], v154 offset:3072
	ds_read_b128 v[158:161], v178
	ds_read_b128 v[162:165], v178 offset:1024
	ds_read_b128 v[168:171], v178 offset:2048
	ds_read_b128 v[178:181], v178 offset:3072
	s_add_u32 s46, s46, s20
	s_addc_u32 s47, s47, 0
	s_mov_b32 m0, s77
	v_lshl_add_u64 v[226:227], s[46:47], 0, v[130:131]
	ds_read_b128 v[182:185], v177 offset:32768
	ds_read_b128 v[186:189], v177 offset:33792
	ds_read_b128 v[190:193], v177 offset:34816
	ds_read_b128 v[194:197], v177 offset:35840
	ds_read_b128 v[198:201], v177 offset:36864
	ds_read_b128 v[202:205], v177 offset:37888
	ds_read_b128 v[206:209], v177 offset:38912
	ds_read_b128 v[216:219], v177 offset:39936
	global_load_lds_dwordx4 v[226:227], off
	v_lshl_add_u64 v[226:227], s[46:47], 0, v[132:133]
	s_mov_b32 m0, s78
	s_nop 0
	global_load_lds_dwordx4 v[226:227], off
	s_waitcnt vmcnt(8)
	s_waitcnt lgkmcnt(0)
	s_barrier
	s_setprio 1
	s_waitcnt lgkmcnt(0)
	v_mfma_f32_16x16x32_bf16 v[126:129], v[142:145], v[182:185], v[126:129]
	v_mfma_f32_16x16x32_bf16 v[122:125], v[150:153], v[182:185], v[122:125]
	v_mfma_f32_16x16x32_bf16 v[110:113], v[142:145], v[190:193], v[110:113]
	v_mfma_f32_16x16x32_bf16 v[106:109], v[150:153], v[190:193], v[106:109]
	v_mfma_f32_16x16x32_bf16 v[92:95], v[142:145], v[198:201], v[92:95]
	v_mfma_f32_16x16x32_bf16 v[88:91], v[150:153], v[198:201], v[88:91]
	v_mfma_f32_16x16x32_bf16 v[76:79], v[142:145], v[206:209], v[76:79]
	v_mfma_f32_16x16x32_bf16 v[72:75], v[150:153], v[206:209], v[72:75]
	v_mfma_f32_16x16x32_bf16 v[126:129], v[146:149], v[186:189], v[126:129]
	v_mfma_f32_16x16x32_bf16 v[122:125], v[154:157], v[186:189], v[122:125]
	v_mfma_f32_16x16x32_bf16 v[110:113], v[146:149], v[194:197], v[110:113]
	v_mfma_f32_16x16x32_bf16 v[106:109], v[154:157], v[194:197], v[106:109]
	v_mfma_f32_16x16x32_bf16 v[92:95], v[146:149], v[202:205], v[92:95]
	v_mfma_f32_16x16x32_bf16 v[88:91], v[154:157], v[202:205], v[88:91]
	v_mfma_f32_16x16x32_bf16 v[76:79], v[146:149], v[216:219], v[76:79]
	v_mfma_f32_16x16x32_bf16 v[72:75], v[154:157], v[216:219], v[72:75]
	v_mfma_f32_16x16x32_bf16 v[118:121], v[158:161], v[182:185], v[118:121]
	v_mfma_f32_16x16x32_bf16 v[114:117], v[168:171], v[182:185], v[114:117]
	v_mfma_f32_16x16x32_bf16 v[102:105], v[158:161], v[190:193], v[102:105]
	v_mfma_f32_16x16x32_bf16 v[98:101], v[168:171], v[190:193], v[98:101]
	v_mfma_f32_16x16x32_bf16 v[84:87], v[158:161], v[198:201], v[84:87]
	v_mfma_f32_16x16x32_bf16 v[80:83], v[168:171], v[198:201], v[80:83]
	v_mfma_f32_16x16x32_bf16 v[68:71], v[158:161], v[206:209], v[68:71]
	v_mfma_f32_16x16x32_bf16 v[64:67], v[168:171], v[206:209], v[64:67]
	v_mfma_f32_16x16x32_bf16 v[118:121], v[162:165], v[186:189], v[118:121]
	v_mfma_f32_16x16x32_bf16 v[114:117], v[178:181], v[186:189], v[114:117]
	v_mfma_f32_16x16x32_bf16 v[102:105], v[162:165], v[194:197], v[102:105]
	v_mfma_f32_16x16x32_bf16 v[98:101], v[178:181], v[194:197], v[98:101]
	v_mfma_f32_16x16x32_bf16 v[84:87], v[162:165], v[202:205], v[84:87]
	v_mfma_f32_16x16x32_bf16 v[80:83], v[178:181], v[202:205], v[80:83]
	v_mfma_f32_16x16x32_bf16 v[68:71], v[162:165], v[216:219], v[68:71]
	v_mfma_f32_16x16x32_bf16 v[64:67], v[178:181], v[216:219], v[64:67]
	s_setprio 0
	s_barrier
	s_add_i32 s46, s86, s71
	v_lshl_add_u64 v[172:173], v[172:173], 0, s[94:95]
	s_mov_b32 m0, s46
	ds_read_b128 v[182:185], v177 offset:49152
	ds_read_b128 v[186:189], v177 offset:50176
	ds_read_b128 v[190:193], v177 offset:51200
	ds_read_b128 v[194:197], v177 offset:52224
	ds_read_b128 v[198:201], v177 offset:53248
	ds_read_b128 v[202:205], v177 offset:54272
	ds_read_b128 v[206:209], v177 offset:55296
	ds_read_b128 v[216:219], v177 offset:56320
	global_load_lds_dwordx4 v[172:173], off
	v_lshl_add_u64 v[172:173], v[210:211], 0, s[94:95]
	s_add_i32 m0, s46, 0x2000
	s_add_i32 s46, s87, s71
	global_load_lds_dwordx4 v[172:173], off
	v_lshl_add_u64 v[172:173], v[212:213], 0, s[94:95]
	s_mov_b32 m0, s46
	s_nop 0
	global_load_lds_dwordx4 v[172:173], off
	v_lshl_add_u64 v[172:173], v[220:221], 0, s[94:95]
	s_add_i32 m0, s46, 0x2000
	s_nop 0
	global_load_lds_dwordx4 v[172:173], off
	v_lshl_add_u64 v[172:173], v[222:223], 0, s[94:95]
	s_mov_b32 m0, s79
	s_nop 0
	global_load_lds_dwordx4 v[172:173], off
	v_lshl_add_u64 v[172:173], v[224:225], 0, s[94:95]
	s_mov_b32 m0, s80
	s_nop 0
	global_load_lds_dwordx4 v[172:173], off
	s_waitcnt vmcnt(8)
	s_waitcnt lgkmcnt(0)
	s_barrier
	s_setprio 1
	s_waitcnt lgkmcnt(0)
	v_mfma_f32_16x16x32_bf16 v[60:63], v[142:145], v[182:185], v[60:63]
	v_mfma_f32_16x16x32_bf16 v[56:59], v[150:153], v[182:185], v[56:59]
	v_mfma_f32_16x16x32_bf16 v[44:47], v[142:145], v[190:193], v[44:47]
	v_mfma_f32_16x16x32_bf16 v[40:43], v[150:153], v[190:193], v[40:43]
	v_mfma_f32_16x16x32_bf16 v[28:31], v[142:145], v[198:201], v[28:31]
	v_mfma_f32_16x16x32_bf16 v[24:27], v[150:153], v[198:201], v[24:27]
	v_mfma_f32_16x16x32_bf16 v[12:15], v[142:145], v[206:209], v[12:15]
	v_mfma_f32_16x16x32_bf16 v[8:11], v[150:153], v[206:209], v[8:11]
	v_mfma_f32_16x16x32_bf16 v[60:63], v[146:149], v[186:189], v[60:63]
	v_mfma_f32_16x16x32_bf16 v[56:59], v[154:157], v[186:189], v[56:59]
	v_mfma_f32_16x16x32_bf16 v[44:47], v[146:149], v[194:197], v[44:47]
	v_mfma_f32_16x16x32_bf16 v[40:43], v[154:157], v[194:197], v[40:43]
	v_mfma_f32_16x16x32_bf16 v[28:31], v[146:149], v[202:205], v[28:31]
	v_mfma_f32_16x16x32_bf16 v[24:27], v[154:157], v[202:205], v[24:27]
	v_mfma_f32_16x16x32_bf16 v[12:15], v[146:149], v[216:219], v[12:15]
	v_mfma_f32_16x16x32_bf16 v[8:11], v[154:157], v[216:219], v[8:11]
	v_mfma_f32_16x16x32_bf16 v[52:55], v[158:161], v[182:185], v[52:55]
	v_mfma_f32_16x16x32_bf16 v[48:51], v[168:171], v[182:185], v[48:51]
	v_mfma_f32_16x16x32_bf16 v[36:39], v[158:161], v[190:193], v[36:39]
	v_mfma_f32_16x16x32_bf16 v[32:35], v[168:171], v[190:193], v[32:35]
	v_mfma_f32_16x16x32_bf16 v[20:23], v[158:161], v[198:201], v[20:23]
	v_mfma_f32_16x16x32_bf16 v[16:19], v[168:171], v[198:201], v[16:19]
	v_mfma_f32_16x16x32_bf16 v[4:7], v[158:161], v[206:209], v[4:7]
	v_mfma_f32_16x16x32_bf16 v[0:3], v[168:171], v[206:209], v[0:3]
	v_mfma_f32_16x16x32_bf16 v[52:55], v[162:165], v[186:189], v[52:55]
	v_mfma_f32_16x16x32_bf16 v[48:51], v[178:181], v[186:189], v[48:51]
	v_mfma_f32_16x16x32_bf16 v[36:39], v[162:165], v[194:197], v[36:39]
	v_mfma_f32_16x16x32_bf16 v[32:35], v[178:181], v[194:197], v[32:35]
	v_mfma_f32_16x16x32_bf16 v[20:23], v[162:165], v[202:205], v[20:23]
	v_mfma_f32_16x16x32_bf16 v[16:19], v[178:181], v[202:205], v[16:19]
	v_mfma_f32_16x16x32_bf16 v[4:7], v[162:165], v[216:219], v[4:7]
	v_mfma_f32_16x16x32_bf16 v[0:3], v[178:181], v[216:219], v[0:3]
	s_setprio 0
	s_barrier
	s_add_u32 s36, s36, 0x100
	s_addc_u32 s37, s37, 0
	s_add_u32 s48, s48, 0x100
	s_addc_u32 s49, s49, 0
	s_cmp_ge_u32 s84, s2
	s_mov_b32 s46, s84
	s_cbranch_scc0 .LBB0_511
	s_branch .Lz511_exit

.Lz511_exit:
	s_and_b64 vcc, exec, s[26:27]
	s_cbranch_vccz .LBB0_514
	s_barrier

.LBB0_653:
	s_add_u32 s34, s34, 0x80
	s_addc_u32 s35, s35, 0
	s_add_u32 s46, s36, 0x100
	s_addc_u32 s47, s37, 0
	s_mov_b32 s36, 0
	s_add_i32 s56, s36, 2
	s_add_u32 s57, s34, 0x80
	s_addc_u32 s37, s35, 0
	s_add_i32 s84, 0, 0x10000
	s_cmp_eq_u32 s2, s36
	s_cselect_b32 s37, s9, s37
	s_cselect_b32 s36, s8, s57
	s_cselect_b32 vcc_hi, s31, s47
	s_cselect_b32 vcc_lo, s30, s46
	s_add_i32 s57, 0, 0x14000
	v_add_u32_e32 v154, s84, v174
	v_add_u32_e32 v172, s57, v174
	ds_read_b128 v[142:145], v154
	ds_read_b128 v[146:149], v154 offset:1024
	ds_read_b128 v[150:153], v154 offset:2048
	ds_read_b128 v[154:157], v154 offset:3072
	ds_read_b128 v[158:161], v172
	ds_read_b128 v[162:165], v172 offset:1024
	ds_read_b128 v[168:171], v172 offset:2048
	ds_read_b128 v[178:181], v172 offset:3072
	v_lshl_add_u64 v[172:173], s[34:35], 0, v[138:139]
	s_add_i32 m0, s77, 0xc000
	ds_read_b128 v[182:185], v177
	ds_read_b128 v[186:189], v177 offset:1024
	ds_read_b128 v[190:193], v177 offset:2048
	ds_read_b128 v[194:197], v177 offset:3072
	ds_read_b128 v[198:201], v177 offset:4096
	ds_read_b128 v[202:205], v177 offset:5120
	ds_read_b128 v[206:209], v177 offset:6144
	ds_read_b128 v[216:219], v177 offset:7168
	global_load_lds_dwordx4 v[172:173], off
	v_lshl_add_u64 v[172:173], s[34:35], 0, v[140:141]
	s_add_i32 m0, s77, 0xe000
	s_nop 0
	global_load_lds_dwordx4 v[172:173], off
	s_waitcnt vmcnt(8)
	s_waitcnt lgkmcnt(0)
	s_barrier
	s_setprio 1
	s_waitcnt lgkmcnt(0)
	v_mfma_f32_16x16x32_f16 v[126:129], v[142:145], v[182:185], 0
	v_mfma_f32_16x16x32_f16 v[122:125], v[150:153], v[182:185], 0
	v_mfma_f32_16x16x32_f16 v[110:113], v[142:145], v[190:193], 0
	v_mfma_f32_16x16x32_f16 v[106:109], v[150:153], v[190:193], 0
	v_mfma_f32_16x16x32_f16 v[92:95], v[142:145], v[198:201], 0
	v_mfma_f32_16x16x32_f16 v[88:91], v[150:153], v[198:201], 0
	v_mfma_f32_16x16x32_f16 v[76:79], v[142:145], v[206:209], 0
	v_mfma_f32_16x16x32_f16 v[72:75], v[150:153], v[206:209], 0
	v_mfma_f32_16x16x32_f16 v[126:129], v[146:149], v[186:189], v[126:129]
	v_mfma_f32_16x16x32_f16 v[122:125], v[154:157], v[186:189], v[122:125]
	v_mfma_f32_16x16x32_f16 v[110:113], v[146:149], v[194:197], v[110:113]
	v_mfma_f32_16x16x32_f16 v[106:109], v[154:157], v[194:197], v[106:109]
	v_mfma_f32_16x16x32_f16 v[92:95], v[146:149], v[202:205], v[92:95]
	v_mfma_f32_16x16x32_f16 v[88:91], v[154:157], v[202:205], v[88:91]
	v_mfma_f32_16x16x32_f16 v[76:79], v[146:149], v[216:219], v[76:79]
	v_mfma_f32_16x16x32_f16 v[72:75], v[154:157], v[216:219], v[72:75]
	v_mfma_f32_16x16x32_f16 v[118:121], v[158:161], v[182:185], 0
	v_mfma_f32_16x16x32_f16 v[114:117], v[168:171], v[182:185], 0
	v_mfma_f32_16x16x32_f16 v[102:105], v[158:161], v[190:193], 0
	v_mfma_f32_16x16x32_f16 v[98:101], v[168:171], v[190:193], 0
	v_mfma_f32_16x16x32_f16 v[84:87], v[158:161], v[198:201], 0
	v_mfma_f32_16x16x32_f16 v[80:83], v[168:171], v[198:201], 0
	v_mfma_f32_16x16x32_f16 v[68:71], v[158:161], v[206:209], 0
	v_mfma_f32_16x16x32_f16 v[64:67], v[168:171], v[206:209], 0
	v_mfma_f32_16x16x32_f16 v[118:121], v[162:165], v[186:189], v[118:121]
	v_mfma_f32_16x16x32_f16 v[114:117], v[178:181], v[186:189], v[114:117]
	v_mfma_f32_16x16x32_f16 v[102:105], v[162:165], v[194:197], v[102:105]
	v_mfma_f32_16x16x32_f16 v[98:101], v[178:181], v[194:197], v[98:101]
	v_mfma_f32_16x16x32_f16 v[84:87], v[162:165], v[202:205], v[84:87]
	v_mfma_f32_16x16x32_f16 v[80:83], v[178:181], v[202:205], v[80:83]
	v_mfma_f32_16x16x32_f16 v[68:71], v[162:165], v[216:219], v[68:71]
	v_mfma_f32_16x16x32_f16 v[64:67], v[178:181], v[216:219], v[64:67]
	s_setprio 0
	s_barrier
	s_add_i32 s84, s84, s76
	v_lshl_add_u64 v[172:173], vcc, 0, v[96:97]
	s_mov_b32 m0, s84
	ds_read_b128 v[182:185], v177 offset:16384
	ds_read_b128 v[186:189], v177 offset:17408
	ds_read_b128 v[190:193], v177 offset:18432
	ds_read_b128 v[194:197], v177 offset:19456
	ds_read_b128 v[198:201], v177 offset:20480
	ds_read_b128 v[202:205], v177 offset:21504
	ds_read_b128 v[206:209], v177 offset:22528
	ds_read_b128 v[216:219], v177 offset:23552
	global_load_lds_dwordx4 v[172:173], off
	s_add_i32 m0, s84, 0x2000
	v_lshl_add_u64 v[210:211], vcc, 0, v[134:135]
	s_add_u32 vcc_lo, vcc_lo, s71
	s_addc_u32 vcc_hi, vcc_hi, 0
	s_add_i32 s57, s57, s76
	global_load_lds_dwordx4 v[210:211], off
	v_lshl_add_u64 v[212:213], vcc, 0, v[96:97]
	s_mov_b32 m0, s57
	v_lshl_add_u64 v[220:221], vcc, 0, v[134:135]
	global_load_lds_dwordx4 v[212:213], off
	s_add_i32 m0, s57, 0x2000
	v_lshl_add_u64 v[222:223], s[36:37], 0, v[130:131]
	global_load_lds_dwordx4 v[220:221], off
	s_mov_b32 m0, s77
	v_lshl_add_u64 v[224:225], s[36:37], 0, v[132:133]
	global_load_lds_dwordx4 v[222:223], off
	s_mov_b32 m0, s78
	s_nop 0
	global_load_lds_dwordx4 v[224:225], off
	s_waitcnt vmcnt(8)
	s_waitcnt lgkmcnt(0)
	s_barrier
	s_setprio 1
	s_waitcnt lgkmcnt(0)
	v_mfma_f32_16x16x32_f16 v[60:63], v[142:145], v[182:185], 0
	v_mfma_f32_16x16x32_f16 v[56:59], v[150:153], v[182:185], 0
	v_mfma_f32_16x16x32_f16 v[44:47], v[142:145], v[190:193], 0
	v_mfma_f32_16x16x32_f16 v[40:43], v[150:153], v[190:193], 0
	v_mfma_f32_16x16x32_f16 v[28:31], v[142:145], v[198:201], 0
	v_mfma_f32_16x16x32_f16 v[24:27], v[150:153], v[198:201], 0
	v_mfma_f32_16x16x32_f16 v[12:15], v[142:145], v[206:209], 0
	v_mfma_f32_16x16x32_f16 v[8:11], v[150:153], v[206:209], 0
	v_mfma_f32_16x16x32_f16 v[60:63], v[146:149], v[186:189], v[60:63]
	v_mfma_f32_16x16x32_f16 v[56:59], v[154:157], v[186:189], v[56:59]
	v_mfma_f32_16x16x32_f16 v[44:47], v[146:149], v[194:197], v[44:47]
	v_mfma_f32_16x16x32_f16 v[40:43], v[154:157], v[194:197], v[40:43]
	v_mfma_f32_16x16x32_f16 v[28:31], v[146:149], v[202:205], v[28:31]
	v_mfma_f32_16x16x32_f16 v[24:27], v[154:157], v[202:205], v[24:27]
	v_mfma_f32_16x16x32_f16 v[12:15], v[146:149], v[216:219], v[12:15]
	v_mfma_f32_16x16x32_f16 v[8:11], v[154:157], v[216:219], v[8:11]
	v_mfma_f32_16x16x32_f16 v[52:55], v[158:161], v[182:185], 0
	v_mfma_f32_16x16x32_f16 v[48:51], v[168:171], v[182:185], 0
	v_mfma_f32_16x16x32_f16 v[36:39], v[158:161], v[190:193], 0
	v_mfma_f32_16x16x32_f16 v[32:35], v[168:171], v[190:193], 0
	v_mfma_f32_16x16x32_f16 v[20:23], v[158:161], v[198:201], 0
	v_mfma_f32_16x16x32_f16 v[16:19], v[168:171], v[198:201], 0
	v_mfma_f32_16x16x32_f16 v[4:7], v[158:161], v[206:209], 0
	v_mfma_f32_16x16x32_f16 v[0:3], v[168:171], v[206:209], 0
	v_mfma_f32_16x16x32_f16 v[52:55], v[162:165], v[186:189], v[52:55]
	v_mfma_f32_16x16x32_f16 v[48:51], v[178:181], v[186:189], v[48:51]
	v_mfma_f32_16x16x32_f16 v[36:39], v[162:165], v[194:197], v[36:39]
	v_mfma_f32_16x16x32_f16 v[32:35], v[178:181], v[194:197], v[32:35]
	v_mfma_f32_16x16x32_f16 v[20:23], v[162:165], v[202:205], v[20:23]
	v_mfma_f32_16x16x32_f16 v[16:19], v[178:181], v[202:205], v[16:19]
	v_mfma_f32_16x16x32_f16 v[4:7], v[162:165], v[216:219], v[4:7]
	v_mfma_f32_16x16x32_f16 v[0:3], v[178:181], v[216:219], v[0:3]
	s_setprio 0
	s_barrier
	s_add_i32 s57, 0, 0x18000
	s_add_i32 s84, 0, 0x1c000
	v_add_u32_e32 v154, s57, v174
	v_add_u32_e32 v178, s84, v174
	ds_read_b128 v[142:145], v154
	ds_read_b128 v[146:149], v154 offset:1024
	ds_read_b128 v[150:153], v154 offset:2048
	ds_read_b128 v[154:157], v154 offset:3072
	ds_read_b128 v[158:161], v178
	ds_read_b128 v[162:165], v178 offset:1024
	ds_read_b128 v[168:171], v178 offset:2048
	ds_read_b128 v[178:181], v178 offset:3072
	s_add_u32 s36, s36, s20
	s_addc_u32 s37, s37, 0
	s_mov_b32 m0, s79
	v_lshl_add_u64 v[226:227], s[36:37], 0, v[130:131]
	ds_read_b128 v[182:185], v177 offset:32768
	ds_read_b128 v[186:189], v177 offset:33792
	ds_read_b128 v[190:193], v177 offset:34816
	ds_read_b128 v[194:197], v177 offset:35840
	ds_read_b128 v[198:201], v177 offset:36864
	ds_read_b128 v[202:205], v177 offset:37888
	ds_read_b128 v[206:209], v177 offset:38912
	ds_read_b128 v[216:219], v177 offset:39936
	global_load_lds_dwordx4 v[226:227], off
	v_lshl_add_u64 v[226:227], s[36:37], 0, v[132:133]
	s_mov_b32 m0, s80
	s_nop 0
	global_load_lds_dwordx4 v[226:227], off
	s_waitcnt vmcnt(8)
	s_waitcnt lgkmcnt(0)
	s_barrier
	s_setprio 1
	s_waitcnt lgkmcnt(0)
	v_mfma_f32_16x16x32_f16 v[126:129], v[142:145], v[182:185], v[126:129]
	v_mfma_f32_16x16x32_f16 v[122:125], v[150:153], v[182:185], v[122:125]
	v_mfma_f32_16x16x32_f16 v[110:113], v[142:145], v[190:193], v[110:113]
	v_mfma_f32_16x16x32_f16 v[106:109], v[150:153], v[190:193], v[106:109]
	v_mfma_f32_16x16x32_f16 v[92:95], v[142:145], v[198:201], v[92:95]
	v_mfma_f32_16x16x32_f16 v[88:91], v[150:153], v[198:201], v[88:91]
	v_mfma_f32_16x16x32_f16 v[76:79], v[142:145], v[206:209], v[76:79]
	v_mfma_f32_16x16x32_f16 v[72:75], v[150:153], v[206:209], v[72:75]
	v_mfma_f32_16x16x32_f16 v[126:129], v[146:149], v[186:189], v[126:129]
	v_mfma_f32_16x16x32_f16 v[122:125], v[154:157], v[186:189], v[122:125]
	v_mfma_f32_16x16x32_f16 v[110:113], v[146:149], v[194:197], v[110:113]
	v_mfma_f32_16x16x32_f16 v[106:109], v[154:157], v[194:197], v[106:109]
	v_mfma_f32_16x16x32_f16 v[92:95], v[146:149], v[202:205], v[92:95]
	v_mfma_f32_16x16x32_f16 v[88:91], v[154:157], v[202:205], v[88:91]
	v_mfma_f32_16x16x32_f16 v[76:79], v[146:149], v[216:219], v[76:79]
	v_mfma_f32_16x16x32_f16 v[72:75], v[154:157], v[216:219], v[72:75]
	v_mfma_f32_16x16x32_f16 v[118:121], v[158:161], v[182:185], v[118:121]
	v_mfma_f32_16x16x32_f16 v[114:117], v[168:171], v[182:185], v[114:117]
	v_mfma_f32_16x16x32_f16 v[102:105], v[158:161], v[190:193], v[102:105]
	v_mfma_f32_16x16x32_f16 v[98:101], v[168:171], v[190:193], v[98:101]
	v_mfma_f32_16x16x32_f16 v[84:87], v[158:161], v[198:201], v[84:87]
	v_mfma_f32_16x16x32_f16 v[80:83], v[168:171], v[198:201], v[80:83]
	v_mfma_f32_16x16x32_f16 v[68:71], v[158:161], v[206:209], v[68:71]
	v_mfma_f32_16x16x32_f16 v[64:67], v[168:171], v[206:209], v[64:67]
	v_mfma_f32_16x16x32_f16 v[118:121], v[162:165], v[186:189], v[118:121]
	v_mfma_f32_16x16x32_f16 v[114:117], v[178:181], v[186:189], v[114:117]
	v_mfma_f32_16x16x32_f16 v[102:105], v[162:165], v[194:197], v[102:105]
	v_mfma_f32_16x16x32_f16 v[98:101], v[178:181], v[194:197], v[98:101]
	v_mfma_f32_16x16x32_f16 v[84:87], v[162:165], v[202:205], v[84:87]
	v_mfma_f32_16x16x32_f16 v[80:83], v[178:181], v[202:205], v[80:83]
	v_mfma_f32_16x16x32_f16 v[68:71], v[162:165], v[216:219], v[68:71]
	v_mfma_f32_16x16x32_f16 v[64:67], v[178:181], v[216:219], v[64:67]
	s_setprio 0
	s_barrier
	s_add_i32 s36, s57, s76
	v_lshl_add_u64 v[172:173], v[172:173], 0, s[94:95]
	s_mov_b32 m0, s36
	ds_read_b128 v[182:185], v177 offset:49152
	ds_read_b128 v[186:189], v177 offset:50176
	ds_read_b128 v[190:193], v177 offset:51200
	ds_read_b128 v[194:197], v177 offset:52224
	ds_read_b128 v[198:201], v177 offset:53248
	ds_read_b128 v[202:205], v177 offset:54272
	ds_read_b128 v[206:209], v177 offset:55296
	ds_read_b128 v[216:219], v177 offset:56320
	global_load_lds_dwordx4 v[172:173], off
	v_lshl_add_u64 v[172:173], v[210:211], 0, s[94:95]
	s_add_i32 m0, s36, 0x2000
	s_add_i32 s36, s84, s76
	global_load_lds_dwordx4 v[172:173], off
	v_lshl_add_u64 v[172:173], v[212:213], 0, s[94:95]
	s_mov_b32 m0, s36
	s_nop 0
	global_load_lds_dwordx4 v[172:173], off
	v_lshl_add_u64 v[172:173], v[220:221], 0, s[94:95]
	s_add_i32 m0, s36, 0x2000
	s_nop 0
	global_load_lds_dwordx4 v[172:173], off
	v_lshl_add_u64 v[172:173], v[222:223], 0, s[94:95]
	s_mov_b32 m0, s81
	s_nop 0
	global_load_lds_dwordx4 v[172:173], off
	v_lshl_add_u64 v[172:173], v[224:225], 0, s[94:95]
	s_mov_b32 m0, s99
	s_nop 0
	global_load_lds_dwordx4 v[172:173], off
	s_waitcnt vmcnt(8)
	s_waitcnt lgkmcnt(0)
	s_barrier
	s_setprio 1
	s_waitcnt lgkmcnt(0)
	v_mfma_f32_16x16x32_f16 v[60:63], v[142:145], v[182:185], v[60:63]
	v_mfma_f32_16x16x32_f16 v[56:59], v[150:153], v[182:185], v[56:59]
	v_mfma_f32_16x16x32_f16 v[44:47], v[142:145], v[190:193], v[44:47]
	v_mfma_f32_16x16x32_f16 v[40:43], v[150:153], v[190:193], v[40:43]
	v_mfma_f32_16x16x32_f16 v[28:31], v[142:145], v[198:201], v[28:31]
	v_mfma_f32_16x16x32_f16 v[24:27], v[150:153], v[198:201], v[24:27]
	v_mfma_f32_16x16x32_f16 v[12:15], v[142:145], v[206:209], v[12:15]
	v_mfma_f32_16x16x32_f16 v[8:11], v[150:153], v[206:209], v[8:11]
	v_mfma_f32_16x16x32_f16 v[60:63], v[146:149], v[186:189], v[60:63]
	v_mfma_f32_16x16x32_f16 v[56:59], v[154:157], v[186:189], v[56:59]
	v_mfma_f32_16x16x32_f16 v[44:47], v[146:149], v[194:197], v[44:47]
	v_mfma_f32_16x16x32_f16 v[40:43], v[154:157], v[194:197], v[40:43]
	v_mfma_f32_16x16x32_f16 v[28:31], v[146:149], v[202:205], v[28:31]
	v_mfma_f32_16x16x32_f16 v[24:27], v[154:157], v[202:205], v[24:27]
	v_mfma_f32_16x16x32_f16 v[12:15], v[146:149], v[216:219], v[12:15]
	v_mfma_f32_16x16x32_f16 v[8:11], v[154:157], v[216:219], v[8:11]
	v_mfma_f32_16x16x32_f16 v[52:55], v[158:161], v[182:185], v[52:55]
	v_mfma_f32_16x16x32_f16 v[48:51], v[168:171], v[182:185], v[48:51]
	v_mfma_f32_16x16x32_f16 v[36:39], v[158:161], v[190:193], v[36:39]
	v_mfma_f32_16x16x32_f16 v[32:35], v[168:171], v[190:193], v[32:35]
	v_mfma_f32_16x16x32_f16 v[20:23], v[158:161], v[198:201], v[20:23]
	v_mfma_f32_16x16x32_f16 v[16:19], v[168:171], v[198:201], v[16:19]
	v_mfma_f32_16x16x32_f16 v[4:7], v[158:161], v[206:209], v[4:7]
	v_mfma_f32_16x16x32_f16 v[0:3], v[168:171], v[206:209], v[0:3]
	v_mfma_f32_16x16x32_f16 v[52:55], v[162:165], v[186:189], v[52:55]
	v_mfma_f32_16x16x32_f16 v[48:51], v[178:181], v[186:189], v[48:51]
	v_mfma_f32_16x16x32_f16 v[36:39], v[162:165], v[194:197], v[36:39]
	v_mfma_f32_16x16x32_f16 v[32:35], v[178:181], v[194:197], v[32:35]
	v_mfma_f32_16x16x32_f16 v[20:23], v[162:165], v[202:205], v[20:23]
	v_mfma_f32_16x16x32_f16 v[16:19], v[178:181], v[202:205], v[16:19]
	v_mfma_f32_16x16x32_f16 v[4:7], v[162:165], v[216:219], v[4:7]
	v_mfma_f32_16x16x32_f16 v[0:3], v[178:181], v[216:219], v[0:3]
	s_setprio 0
	s_barrier
	s_add_u32 s34, s34, 0x100
	s_addc_u32 s35, s35, 0
	s_add_u32 s46, s46, 0x100
	s_addc_u32 s47, s47, 0
	s_cmp_ge_u32 s56, s70
	s_mov_b32 s36, s56
	s_cbranch_scc0 .LBB0_654
	s_branch .Lz654_exit
